# attention loop edges trimmed: dead compare/branch pairs and lgkmcnt waits left over from register staging removed
# speedup vs baseline: 1.0073x; 1.0039x over previous
; __device__ __forceinline__ void attn_qk(const u16* kp, const bf16x8 (&qa)[6], f32x16& s0, f32x16& s1) {
; #pragma unroll
;   for (int ks = 0; ks < 6; ++ks) {
;     bf16x8 k0 = *(const bf16x8*)(kp + ks * 16);
;     bf16x8 k1 = *(const bf16x8*)(kp + 32 * KLD + ks * 16);
;     s0 = mfma32(k0, qa[ks], s0);
;     s1 = mfma32(k1, qa[ks], s1);
;   }
; }
; __device__ __forceinline__ void attn_tile(const u16* sb, const bf16x8 (&qa)[6], f32x16& o0, f32x16& o1, f32x16& lacc,
;                                           float& m, bool& mz, int r, int h, bool first) {
;   const u16* kp = sb + r * KLD + h * 8;
;   f32x16 s0, s1;
;   __builtin_amdgcn_s_setprio(1);
;   if (mz) {
; #pragma unroll
;     for (int i = 0; i < 16; ++i) { s0[i] = 0.f; s1[i] = 0.f; }
;     attn_qk(kp, qa, s0, s1);
;   } else {
; #pragma unroll
;     for (int i = 0; i < 16; ++i) { s0[i] = -m; s1[i] = -m; }
;     attn_qk(kp, qa, s0, s1);
;   }
; __device__ void item_attn(PP p, int qb, int b, int hh, u16* lds) {
;     ...
;   for (int kt = 0; kt < ntiles; kt += 2) {
;     if (kt + 2 < ntiles) as_load(B, kg, vg, kt + 2);
;     attn_tile(lds, qa, oa0, oa1, lacc, ma, mz, r, h, kt == 0);
;     as_store(A, lds + ATT_STAGE, kl0, kl1, kl2, vl);
;     __syncthreads();
.LBB0_455:
	s_add_u32 s46, s46, 0x4000
	s_addc_u32 s47, s47, 0
	s_add_u32 s42, s42, 0x6000
	s_addc_u32 s43, s43, 0
	s_add_i32 s45, s45, 2
	s_cmp_lt_i32 s58, s44
	s_barrier
	s_cbranch_scc0 .LBB0_477
.LBB0_456:
	s_add_u32 s60, s46, 0x6000
	s_addc_u32 s61, s47, 0
	s_add_u32 m0, s62, 35840
	s_nop 0
	global_load_lds_dwordx4 v213, s[60:61]
	s_add_u32 s60, s60, 0x1000
	s_addc_u32 s61, s61, 0
	s_add_u32 m0, s62, 39936
	s_nop 0
	global_load_lds_dwordx4 v213, s[60:61]
	s_add_i32 s58, s45, -1
	s_cmp_lt_i32 s58, s44
	s_cselect_b64 s[0:1], -1, 0
.LBB0_458:
	ds_read_b128 v[214:217], v90
	ds_read_b128 v[218:221], v90 offset:6144
	ds_read_b128 v[222:225], v91
	ds_read_b128 v[226:229], v91 offset:6144
	ds_read_b128 v[230:233], v92
	ds_read_b128 v[234:237], v92 offset:6144
	ds_read_b128 v[238:241], v93
	ds_read_b128 v[242:245], v93 offset:6144
	ds_read_b128 v[246:249], v94
	ds_read_b128 v[250:253], v94 offset:6144
	ds_read_b128 v[142:145], v95
	ds_read_b128 v[146:149], v95 offset:6144
	s_setprio 1
	s_cmp_lg_u64 s[48:49], 0
	s_cbranch_scc1 .Lmz_e
	v_xor_b32_e32 v34, 0x80000000, v162
	v_mov_b32_e32 v35, v34
	v_mov_b32_e32 v36, v34
	v_mov_b32_e32 v37, v34
	v_mov_b32_e32 v38, v34
	v_mov_b32_e32 v39, v34
	v_mov_b32_e32 v40, v34
	v_mov_b32_e32 v41, v34
	v_mov_b32_e32 v42, v34
	v_mov_b32_e32 v43, v34
	v_mov_b32_e32 v44, v34
	v_mov_b32_e32 v45, v34
	v_mov_b32_e32 v46, v34
	v_mov_b32_e32 v47, v34
	v_mov_b32_e32 v48, v34
	v_mov_b32_e32 v49, v34
	s_waitcnt lgkmcnt(8)
	s_nop 0
	v_mfma_f32_32x32x16_bf16 v[50:65], v[214:217], v[66:69], v[34:49]
	v_mfma_f32_32x32x16_bf16 v[34:49], v[218:221], v[66:69], v[34:49]
	v_mfma_f32_32x32x16_bf16 v[50:65], v[222:225], v[70:73], v[50:65]
	v_mfma_f32_32x32x16_bf16 v[34:49], v[226:229], v[70:73], v[34:49]
	s_waitcnt lgkmcnt(4)
	v_mfma_f32_32x32x16_bf16 v[50:65], v[230:233], v[74:77], v[50:65]
	v_mfma_f32_32x32x16_bf16 v[34:49], v[234:237], v[74:77], v[34:49]
	v_mfma_f32_32x32x16_bf16 v[50:65], v[238:241], v[78:81], v[50:65]
	v_mfma_f32_32x32x16_bf16 v[34:49], v[242:245], v[78:81], v[34:49]
	s_waitcnt lgkmcnt(0)
	v_mfma_f32_32x32x16_bf16 v[50:65], v[246:249], v[82:85], v[50:65]
	v_mfma_f32_32x32x16_bf16 v[34:49], v[250:253], v[82:85], v[34:49]
	v_mfma_f32_32x32x16_bf16 v[50:65], v[142:145], v[86:89], v[50:65]
	v_mfma_f32_32x32x16_bf16 v[34:49], v[146:149], v[86:89], v[34:49]
	s_branch .Lqkd_e

; __device__ __forceinline__ void attn_tile(const u16* sb, const bf16x8 (&qa)[6], f32x16& o0, f32x16& o1, f32x16& lacc,
;                                           float& m, bool& mz, int r, int h, bool first) {
;     ...
;   float pa = 0.f, pb = 0.f, pc = 0.f, pd = 0.f;
; #pragma unroll
;   for (int i = 0; i < 16; ++i) {
;     s0[i] = __builtin_amdgcn_exp2f(s0[i]); s1[i] = __builtin_amdgcn_exp2f(s1[i]);
;     if ((i & 3) == 0) pa += s0[i] + s1[i];
;     else if ((i & 3) == 1) pb += s0[i] + s1[i];
;     else if ((i & 3) == 2) pc += s0[i] + s1[i];
;     else pd += s0[i] + s1[i];
;   }
;   lacc[0] += (pa + pb) + (pc + pd);
;   const u16* vp = sb + 64 * KLD + r * VLD + 8 * h;
;   __builtin_amdgcn_s_setprio(1);
; #pragma unroll
;   for (int kb = 0; kb < 2; ++kb) {
; #pragma unroll
;     for (int s = 0; s < 2; ++s) {
;       const bf16x8 pf = pack_p(kb == 0 ? s0 : s1, 8 * s);
;       const int koff = kb * 32 + 16 * s;
;       const bf16x8 v0 = *(const bf16x8*)(vp + koff);
;       const bf16x8 v1 = *(const bf16x8*)(vp + 32 * VLD + koff);
;       o0 = mfma32(v0, pf, o0);
;       o1 = mfma32(v1, pf, o1);
;     }
;   }
;   __builtin_amdgcn_s_setprio(0);
.LBB0_464:
	v_exp_f32_e32 v147, v53
	v_exp_f32_e32 v149, v37
	v_exp_f32_e32 v145, v57
	v_exp_f32_e32 v53, v41
	v_exp_f32_e32 v143, v61
	v_exp_f32_e32 v45, v45
	v_exp_f32_e32 v37, v65
	v_exp_f32_e32 v41, v49
	v_exp_f32_e32 v146, v34
	v_exp_f32_e32 v152, v35
	v_exp_f32_e32 v153, v36
	v_exp_f32_e32 v144, v38
	v_exp_f32_e32 v150, v39
	v_exp_f32_e32 v151, v40
	v_exp_f32_e32 v142, v42
	v_exp_f32_e32 v38, v43
	v_exp_f32_e32 v39, v44
	v_exp_f32_e32 v36, v46
	v_exp_f32_e32 v34, v47
	v_exp_f32_e32 v35, v48
	v_exp_f32_e32 v148, v50
	v_exp_f32_e32 v50, v51
	v_exp_f32_e32 v51, v52
	v_exp_f32_e32 v52, v54
	v_exp_f32_e32 v48, v55
	v_exp_f32_e32 v49, v56
	v_exp_f32_e32 v44, v58
	v_exp_f32_e32 v46, v59
	v_exp_f32_e32 v47, v60
	v_exp_f32_e32 v40, v62
	v_exp_f32_e32 v42, v63
	v_exp_f32_e32 v43, v64
	s_setprio 1
	v_cvt_pk_bf16_f32 v58, v148, v50
	v_cvt_pk_bf16_f32 v59, v51, v147
	v_cvt_pk_bf16_f32 v60, v52, v48
	v_cvt_pk_bf16_f32 v61, v49, v145
	v_cvt_pk_bf16_f32 v246, v44, v46
	v_cvt_pk_bf16_f32 v247, v47, v143
	v_cvt_pk_bf16_f32 v248, v40, v42
	v_cvt_pk_bf16_f32 v249, v43, v37
	s_waitcnt lgkmcnt(0)
	v_mfma_f32_32x32x16_bf16 v[18:33], v[214:217], v[58:61], v[18:33]
	v_mfma_f32_32x32x16_bf16 v[2:17], v[218:221], v[58:61], v[2:17]
	v_cvt_pk_bf16_f32 v58, v146, v152
	v_cvt_pk_bf16_f32 v59, v153, v149
	v_cvt_pk_bf16_f32 v60, v144, v150
	v_cvt_pk_bf16_f32 v61, v151, v53
	v_mfma_f32_32x32x16_bf16 v[18:33], v[222:225], v[246:249], v[18:33]
	v_mfma_f32_32x32x16_bf16 v[2:17], v[226:229], v[246:249], v[2:17]
	v_cvt_pk_bf16_f32 v246, v142, v38
	v_cvt_pk_bf16_f32 v247, v39, v45
	v_cvt_pk_bf16_f32 v248, v36, v34
	v_cvt_pk_bf16_f32 v249, v35, v41
	v_mfma_f32_32x32x16_bf16 v[18:33], v[230:233], v[58:61], v[18:33]
	v_mfma_f32_32x32x16_bf16 v[2:17], v[234:237], v[58:61], v[2:17]
	v_mfma_f32_32x32x16_bf16 v[18:33], v[238:241], v[246:249], v[18:33]
	v_mfma_f32_32x32x16_bf16 v[2:17], v[242:245], v[246:249], v[2:17]
	s_setprio 0
	v_pk_add_f32 v[50:51], v[50:51], v[152:153]
	v_pk_add_f32 v[48:49], v[48:49], v[150:151]
	v_pk_add_f32 v[38:39], v[46:47], v[38:39]
	v_pk_add_f32 v[48:49], v[48:49], v[50:51]
	v_pk_add_f32 v[34:35], v[42:43], v[34:35]
	v_pk_add_f32 v[38:39], v[38:39], v[48:49]
	v_pk_add_f32 v[42:43], v[52:53], v[144:145]
	v_pk_add_f32 v[34:35], v[34:35], v[38:39]
	v_pk_add_f32 v[38:39], v[148:149], v[146:147]
	v_pk_add_f32 v[36:37], v[40:41], v[36:37]
	v_pk_add_f32 v[38:39], v[42:43], v[38:39]
	v_pk_add_f32 v[42:43], v[44:45], v[142:143]
	s_nop 0
	v_pk_add_f32 v[38:39], v[42:43], v[38:39]
	s_nop 0
	v_pk_add_f32 v[36:37], v[36:37], v[38:39]
	s_nop 0
	v_pk_add_f32 v[34:35], v[34:35], v[36:37]
	s_nop 0
	v_add_f32_e32 v34, v34, v35
	v_add_f32_e32 v136, v136, v34
	s_waitcnt vmcnt(0)
	s_barrier

; __device__ void item_attn(PP p, int qb, int b, int hh, u16* lds) {
;     ...
;     if (kt + 3 < ntiles) as_load(A, kg, vg, kt + 3);
;     if (kt + 1 < my_ntiles) attn_tile(lds + ATT_STAGE, qa, oa0, oa1, lacc, ma, mz, r, h, false);
;     if (kt + 2 < ntiles) as_store(B, lds, kl0, kl1, kl2, vl);
;     __syncthreads();
.LBB0_475:
	s_or_b64 exec, exec, s[40:41]
	s_waitcnt vmcnt(0)
	s_branch .LBB0_455
